# dense attention: S^T accumulator used directly as the P.V A operand (8 v_permlane32_swap per tile removed; V staged without the key bit2/3 swap so tr-reads match the accumulator k order)
# speedup vs baseline: 1.0034x; 1.0034x over previous
; #define SLOAD(i, k0) do { sr_[i].vs0 = St::ld8(&Vh[(long)((k0) + sr) * LDK + sc]); sr_[i].vs1 = St::ld8(&Vh[(long)((k0) + 32 + sr) * LDK + sc]); \
;     sr_[i].ks0 = St::ld8(&Kh[(long)((k0) + sr) * LDK + sc]); sr_[i].ks1 = St::ld8(&Kh[(long)((k0) + 32 + sr) * LDK + sc]); } while (0)
; __device__ __forceinline__ int v_st(int k, int c) { const int kk = (k & ~0xC) | ((k & 4) << 1) | ((k & 8) >> 1); return ((kk >> 3) * 4 + (c >> 5)) * 512 + ((kk & 7) * 32 + (c & 31)) * 2; }
; __device__ __forceinline__ int v_rd_base(int lane) { return ((lane & 3) << 3) | (((lane >> 2) & 3) << 6) | (((lane >> 4) & 1) << 5) | (((lane >> 5) & 1) << 8); }
; template <typename TQ>
; __device__ __forceinline__ void attn_dense_body(const TQ* __restrict__ Qb, const bf16* __restrict__ Kh, const bf16* __restrict__ Vh,
;                                                 bf16* __restrict__ Ob, int seq, char* lds, const int tid) {
;     ...
;   const int wid = __builtin_amdgcn_readfirstlane(tid >> 6), lane = tid & 63, r32 = lane & 31, hi = lane >> 5;
;   bf16* V_lds = (bf16*)lds; bf16* K_lds = (bf16*)(lds + 2 * SHM_V);
;   float* ws = (float*)(lds + 2 * SHM_V + 2 * SHM_K) + wid * 64; float* li_l = ws; float* al_l = ws + 32;
;   float m_reg = -1e30f, l_reg = 0; f32x16 o[4] = {}; bf16x8 qr[8];
;   const TQ* Qw = Qb + (long)(wid * QBLK + r32) * LDQ + hi * 8;
; #pragma unroll
;   for (int d0 = 0; d0 < 8; ++d0) qr[d0] = SQ::tobf(SQ::ld8(Qw + d0 * 16));
;   const int sr = tid >> 4, sc = (tid & 15) * 8, vst0 = v_st(sr, sc), vst1 = v_st(32 + sr, sc);
;   const int vb0 = (int)(uintptr_t)V_lds + v_rd_base(lane);
;   struct { typename St::T vs0, vs1, ks0, ks1; } sr_[SDEPTH];
;     ...
;   f32x16 pA0, pA1, pB0, pB1; float mnA, mnB, alA, alB; bf16x8 pa0, pa1, pa2, pa3; const int NT = seq / KVBLK;
;   constexpr int SE = 0, SO = SDEPTH - 1;
;   SLOAD(SE, 0); asm volatile("s_waitcnt vmcnt(0)" ::: "memory"); SWRITE(0, SE); __syncthreads();
;   qkt(pA0, pA1, K_lds, qr, r32, hi); partialSM(pA0, pA1, m_reg, mnA, alA);
.LBB0_1528:
	s_lshr_b32 s5, s2, 4
	s_ashr_i32 s4, s2, 7
	s_bfe_u32 s16, s5, 0x10002
	s_ashr_i32 s5, s4, 31
	s_lshl_b64 s[6:7], s[4:5], 12
	s_lshl_b32 s5, s2, 8
	s_and_b32 s5, s5, 0xf00
	s_bfe_u32 s8, s2, 0x30004
	s_or_b32 s5, s6, s5
	s_add_u32 s18, s5, 0x800
	s_addc_u32 s19, s7, 0
	s_mul_i32 s5, s19, 0xc00
	s_mul_hi_u32 s6, s18, 0xc00
	s_add_i32 s6, s6, s5
	s_mul_i32 s5, s18, 0xc00
	s_add_u32 s5, s24, s5
	s_addc_u32 s6, s25, s6
	s_lshl_b32 s15, s8, 7
	s_lshl_b32 s7, s8, 8
	s_add_u32 s8, s5, s7
	s_addc_u32 s9, s6, 0
	s_lshl_b32 s4, s4, 1
	v_mbcnt_lo_u32_b32 v0, -1, 0
	v_mbcnt_hi_u32_b32 v0, -1, v0
	s_or_b32 s16, s16, s4
	v_add_u32_e32 v52, s74, v0
	s_mul_i32 s6, s16, 0x110000
	v_readlane_b32 s4, v254, 14
	v_ashrrev_i32_e32 v16, 4, v52
	s_mul_hi_i32 s7, s16, 0x110000
	v_readlane_b32 s5, v254, 15
	s_add_u32 s4, s4, s6
	v_lshlrev_b32_e32 v22, 3, v52
	v_add_u32_e32 v18, 32, v16
	s_addc_u32 s5, s5, s7
	v_and_b32_e32 v0, 0x78, v22
	v_ashrrev_i32_e32 v17, 31, v16
	v_ashrrev_i32_e32 v19, 31, v18
	s_add_u32 s6, s3, s6
	v_lshlrev_b32_e32 v23, 1, v0
	v_lshlrev_b64 v[48:49], 8, v[16:17]
	s_waitcnt vmcnt(8)
	v_lshlrev_b64 v[12:13], 8, v[18:19]
	s_addc_u32 s7, s11, s7
	v_or_b32_e32 v50, v48, v23
	v_mov_b32_e32 v51, v49
	v_or_b32_e32 v12, v12, v23
	v_lshl_add_u64 v[0:1], s[6:7], 0, v[50:51]
	v_lshl_add_u64 v[4:5], s[6:7], 0, v[12:13]
	s_barrier
	global_load_dwordx4 v[0:3], v[0:1], off
	s_nop 0
	global_load_dwordx4 v[4:7], v[4:5], off
	v_lshl_add_u64 v[8:9], s[4:5], 0, v[50:51]
	global_load_dwordx4 v[8:11], v[8:9], off
	v_lshl_add_u64 v[12:13], s[4:5], 0, v[12:13]
	v_readfirstlane_b32 s17, v52
	global_load_dwordx4 v[12:15], v[12:13], off
	s_ashr_i32 s20, s17, 1
	v_mov_b32_e32 v17, s20
	s_movk_i32 s21, 0xffe0
	v_bfe_u32 v182, v52, 5, 1
	v_bfi_b32 v17, s21, v17, v52
	v_mov_b64_e32 v[20:21], s[8:9]
	s_movk_i32 s8, 0xc00
	v_mad_i64_i32 v[20:21], s[8:9], v17, s8, v[20:21]
	v_lshlrev_b32_e32 v176, 4, v182
	v_lshl_add_u64 v[20:21], v[20:21], 0, v[176:177]
	global_load_dwordx4 v[120:123], v[20:21], off
	global_load_dwordx4 v[112:115], v[20:21], off offset:32
	global_load_dwordx4 v[124:127], v[20:21], off offset:64
	global_load_dwordx4 v[116:119], v[20:21], off offset:96
	global_load_dwordx4 v[108:111], v[20:21], off offset:128
	global_load_dwordx4 v[104:107], v[20:21], off offset:160
	global_load_dwordx4 v[100:103], v[20:21], off offset:192
	global_load_dwordx4 v[96:99], v[20:21], off offset:224
	v_and_b32_e32 v17, 0xfffff0, v16
	v_lshlrev_b32_e32 v19, 1, v16
	v_lshrrev_b32_e32 v24, 1, v16
	v_and_b32_e32 v25, 3, v16
	v_and_or_b32 v17, v16, 8, v17
	v_and_or_b32 v19, v16, 4, v25
	v_and_b32_e32 v24, 0xfffff0, v18
	v_lshlrev_b32_e32 v25, 1, v18
	v_bfe_u32 v22, v22, 5, 2
	v_lshrrev_b32_e32 v17, 1, v17
	v_and_or_b32 v24, v18, 8, v24
	v_or_b32_e32 v17, v17, v22
	v_lshrrev_b32_e32 v24, 1, v24
	v_lshlrev_b32_e32 v19, 6, v19
	v_and_b32_e32 v26, 48, v23
	v_lshlrev_b32_e32 v17, 9, v17
	v_or_b32_e32 v22, v24, v22
	v_or3_b32 v17, v17, v19, v26
	v_lshlrev_b32_e32 v22, 9, v22
	v_or3_b32 v19, v22, v19, v26
	v_add_u32_e32 v188, 0, v17
	v_add_u32_e32 v189, 0, v19
	s_waitcnt vmcnt(0)
	v_and_b32_e32 v183, 31, v52
	v_lshlrev_b32_e32 v53, 4, v52
	v_and_b32_e32 v76, 63, v52
	s_mov_b64 s[36:37], 0x4000
	v_lshl_add_u64 v[62:63], v[50:51], 0, s[36:37]
	s_mov_b64 s[36:37], 0x6000
	s_waitcnt vmcnt(11)
	ds_write_b128 v188, v[0:3]
	s_waitcnt vmcnt(10)
	ds_write_b128 v189, v[4:7]
	v_lshlrev_b32_e32 v0, 8, v16
	v_and_b32_e32 v1, 0xf0, v52
	v_bitop3_b32 v0, v23, v0, v1 bitop3:0xde
	v_add_u32_e32 v190, 0, v0
	v_lshlrev_b32_e32 v0, 8, v18
	s_waitcnt vmcnt(9)
	ds_write_b128 v190, v[8:11] offset:32768
	v_bitop3_b32 v0, v23, v0, v1 bitop3:0xde
	v_lshlrev_b32_e32 v8, 8, v183
	v_and_b32_e32 v9, 0xf0, v53
	v_add_u32_e32 v191, 0, v0
	v_bitop3_b32 v0, v176, v8, v9 bitop3:0xde
	v_add_u32_e32 v192, 0, v0
	s_waitcnt vmcnt(8)
	ds_write_b128 v191, v[12:15] offset:32768
	s_waitcnt lgkmcnt(0)
	s_barrier
	ds_read_b128 v[0:3], v192 offset:32768
	ds_read_b128 v[4:7], v192 offset:40960
	s_waitcnt vmcnt(7) lgkmcnt(1)
	v_mfma_f32_32x32x16_bf16 v[32:47], v[0:3], v[120:123], 0
	v_or_b32_e32 v0, 32, v176
	v_bitop3_b32 v0, v0, v8, v9 bitop3:0xde
	v_add_u32_e32 v199, 0, v0
	v_lshlrev_b32_e32 v10, 3, v76
	v_lshlrev_b32_e32 v12, 1, v52
	v_lshl_add_u64 v[64:65], v[50:51], 0, s[36:37]
	v_lshl_add_u64 v[58:59], s[6:7], 0, v[64:65]
	s_waitcnt lgkmcnt(0)
	v_mfma_f32_32x32x16_bf16 v[16:31], v[4:7], v[120:123], 0
	ds_read_b128 v[0:3], v199 offset:32768
	ds_read_b128 v[4:7], v199 offset:40960
	v_lshl_add_u64 v[66:67], s[4:5], 0, v[64:65]
	s_mov_b64 s[36:37], 0xa000
	s_and_b32 s8, s17, 0x3fffffc0
	s_lshl_b32 s8, s8, 2
	s_add_i32 s8, s8, 0
	s_add_i32 s8, s8, 0x10000
	s_waitcnt vmcnt(6) lgkmcnt(1)
	v_mfma_f32_32x32x16_bf16 v[32:47], v[0:3], v[112:115], v[32:47]
	v_or_b32_e32 v0, 64, v176
	v_bitop3_b32 v0, v0, v8, v9 bitop3:0xde
	v_add_u32_e32 v198, 0, v0
	s_andn2_b32 s20, s20, 31
	s_cmp_lg_u32 0, -1
	s_cselect_b32 s9, 0, 0
	s_mov_b32 s57, s56
	s_waitcnt lgkmcnt(0)
	v_mfma_f32_32x32x16_bf16 v[16:31], v[4:7], v[112:115], v[16:31]
	ds_read_b128 v[0:3], v198 offset:32768
	ds_read_b128 v[4:7], v198 offset:40960
	s_mov_b32 s58, s56
	s_mov_b32 s59, s56
	s_mov_b32 s60, s56
	s_mov_b32 s61, s56
	s_mov_b32 s62, s56
	s_mov_b32 s63, s56
	s_waitcnt vmcnt(5) lgkmcnt(1)
	v_mfma_f32_32x32x16_bf16 v[32:47], v[0:3], v[124:127], v[32:47]
	v_or_b32_e32 v0, 0x60, v176
	v_bitop3_b32 v0, v0, v8, v9 bitop3:0xde
	v_add_u32_e32 v195, 0, v0
	s_mov_b32 s64, s56
	s_mov_b32 s65, s56
	s_mov_b32 s66, s56
	s_mov_b32 s67, s56
	s_waitcnt lgkmcnt(0)
; #define SLOAD(i, k0) do { sr_[i].vs0 = St::ld8(&Vh[(long)((k0) + sr) * LDK + sc]); sr_[i].vs1 = St::ld8(&Vh[(long)((k0) + 32 + sr) * LDK + sc]); \
;     sr_[i].ks0 = St::ld8(&Kh[(long)((k0) + sr) * LDK + sc]); sr_[i].ks1 = St::ld8(&Kh[(long)((k0) + 32 + sr) * LDK + sc]); } while (0)
; #define SWAIT() do { if constexpr (SDEPTH == 2) asm volatile("s_waitcnt vmcnt(4)" ::: "memory"); else asm volatile("s_waitcnt vmcnt(0)" ::: "memory"); } while (0)
; __device__ __forceinline__ void partialSM(f32x16& p0, f32x16& p1, float& m_reg, float& mn, float& alpha) {
;   constexpr float C = SCALE * 1.4426950408889634f;
;   float pmax = p0[0]; for (int r = 1; r < 16; ++r) pmax = fmaxf(pmax, p0[r]); for (int r = 0; r < 16; ++r) pmax = fmaxf(pmax, p1[r]);
;   { auto rr = __builtin_amdgcn_permlane32_swap(__float_as_uint(pmax), __float_as_uint(pmax), false, false);
;     pmax = fmaxf(__uint_as_float(rr[0]), __uint_as_float(rr[1])); }
;   if (__builtin_expect(__all(pmax - m_reg <= THR / SCALE), 1)) { mn = m_reg; alpha = 1.f; }
;   else { mn = fmaxf(m_reg, pmax); alpha = __builtin_amdgcn_exp2f((m_reg - mn) * C); m_reg = mn; }
;   float mnC = -mn * C;
;   for (int r = 0; r < 16; ++r) p0[r] = fmaf(p0[r], C, mnC); for (int r = 0; r < 16; ++r) p1[r] = fmaf(p1[r], C, mnC);
;   for (int r = 0; r < 16; ++r) p0[r] = __builtin_amdgcn_exp2f(p0[r]);
; }
; template <typename TQ>
; __device__ __forceinline__ void attn_dense_body(const TQ* __restrict__ Qb, const bf16* __restrict__ Kh, const bf16* __restrict__ Vh,
;                                                 bf16* __restrict__ Ob, int seq, char* lds, const int tid) {
;     ...
;   qkt(pA0, pA1, K_lds, qr, r32, hi); partialSM(pA0, pA1, m_reg, mnA, alA);
;   SLOAD(SO, KVBLK); if constexpr (SDEPTH == 2) { if (2 < NT) SLOAD(SE, 2 * KVBLK); }
;   SWAIT(); SWRITE(1, SO); __syncthreads();
	v_mfma_f32_32x32x16_bf16 v[16:31], v[4:7], v[124:127], v[16:31]
	ds_read_b128 v[0:3], v195 offset:32768
	ds_read_b128 v[4:7], v195 offset:40960
	s_mov_b32 s68, s56
	s_mov_b32 s69, s56
	s_mov_b32 s70, s56
	s_mov_b32 s71, s56
	v_lshl_add_u32 v184, v183, 2, s8
	v_mov_b32_e32 v185, 0
	s_waitcnt vmcnt(4) lgkmcnt(1)
	v_mfma_f32_32x32x16_bf16 v[32:47], v[0:3], v[116:119], v[32:47]
	v_or_b32_e32 v0, 0x80, v176
	v_bitop3_b32 v0, v0, v8, v9 bitop3:0xde
	v_add_u32_e32 v194, 0, v0
	s_waitcnt lgkmcnt(0)
	v_mfma_f32_32x32x16_bf16 v[16:31], v[4:7], v[116:119], v[16:31]
	ds_read_b128 v[0:3], v194 offset:32768
	ds_read_b128 v[4:7], v194 offset:40960
	s_waitcnt vmcnt(3) lgkmcnt(1)
	v_mfma_f32_32x32x16_bf16 v[32:47], v[0:3], v[108:111], v[32:47]
	v_or_b32_e32 v0, 0xa0, v176
	v_bitop3_b32 v0, v0, v8, v9 bitop3:0xde
	v_add_u32_e32 v193, 0, v0
	ds_read_b128 v[0:3], v193 offset:32768
	s_waitcnt lgkmcnt(1)
	v_mfma_f32_32x32x16_bf16 v[16:31], v[4:7], v[108:111], v[16:31]
	ds_read_b128 v[4:7], v193 offset:40960
	s_waitcnt vmcnt(2) lgkmcnt(1)
	v_mfma_f32_32x32x16_bf16 v[32:47], v[0:3], v[104:107], v[32:47]
	v_and_b32_e32 v0, 0xc0, v53
	v_and_or_b32 v11, v10, 24, v0
	v_or_b32_e32 v0, 0xc0, v176
	v_bitop3_b32 v0, v0, v8, v9 bitop3:0xde
	v_add_u32_e32 v196, 0, v0
	ds_read_b128 v[0:3], v196 offset:32768
	s_waitcnt lgkmcnt(1)
	v_mfma_f32_32x32x16_bf16 v[16:31], v[4:7], v[104:107], v[16:31]
	v_and_b32_e32 v4, 32, v12
	v_and_b32_e32 v5, 0x100, v10
	v_or3_b32 v53, v11, v4, v5
	ds_read_b128 v[4:7], v196 offset:40960
	v_add_u32_e32 v187, s9, v53
	s_waitcnt vmcnt(1) lgkmcnt(1)
	v_mfma_f32_32x32x16_bf16 v[32:47], v[0:3], v[100:103], v[32:47]
	v_or_b32_e32 v0, 0xe0, v176
	v_bitop3_b32 v0, v0, v8, v9 bitop3:0xde
	v_add_u32_e32 v197, 0, v0
	ds_read_b128 v[0:3], v197 offset:32768
	ds_read_b128 v[54:57], v197 offset:40960
	s_waitcnt lgkmcnt(2)
	v_mfma_f32_32x32x16_bf16 v[16:31], v[4:7], v[100:103], v[16:31]
	s_waitcnt vmcnt(0) lgkmcnt(1)
	v_mfma_f32_32x32x16_bf16 v[32:47], v[0:3], v[96:99], v[32:47]
	v_mov_b64_e32 v[0:1], s[56:57]
	v_mov_b64_e32 v[14:15], s[70:71]
	v_mov_b64_e32 v[2:3], s[58:59]
	v_mov_b64_e32 v[4:5], s[60:61]
	v_mov_b64_e32 v[6:7], s[62:63]
	v_mov_b64_e32 v[8:9], s[64:65]
	v_mov_b64_e32 v[10:11], s[66:67]
	s_waitcnt lgkmcnt(0)
	v_mfma_f32_32x32x16_bf16 v[16:31], v[54:57], v[96:99], v[16:31]
	s_nop 2
	v_max_f32_e32 v54, v33, v33
	v_max_f32_e32 v55, v32, v32
	v_max_f32_e32 v54, v55, v54
	v_max3_f32 v54, v54, v34, v35
	v_max3_f32 v54, v54, v36, v37
	v_max3_f32 v54, v54, v38, v39
	v_max3_f32 v54, v54, v40, v41
	v_max3_f32 v54, v54, v42, v43
	v_max3_f32 v54, v54, v44, v45
	v_max3_f32 v54, v54, v46, v47
	v_max3_f32 v70, v54, v16, v17
	v_max3_f32 v70, v70, v18, v19
	v_max3_f32 v70, v70, v20, v21
	v_max3_f32 v70, v70, v22, v23
	v_max3_f32 v70, v70, v24, v25
	v_max3_f32 v70, v70, v26, v27
	v_lshl_add_u64 v[54:55], s[6:7], 0, v[62:63]
	v_lshl_add_u64 v[62:63], s[4:5], 0, v[62:63]
	v_max3_f32 v70, v70, v28, v29
	global_load_dwordx4 v[54:57], v[54:55], off
	s_nop 0
	global_load_dwordx4 v[58:61], v[58:59], off
	s_nop 0
	global_load_dwordx4 v[62:65], v[62:63], off
	s_nop 0
	global_load_dwordx4 v[66:69], v[66:67], off
	v_max3_f32 v77, v70, v30, v31
	v_lshl_add_u64 v[70:71], v[50:51], 0, s[12:13]
	v_lshl_add_u64 v[72:73], s[6:7], 0, v[70:71]
	v_lshl_add_u64 v[50:51], v[50:51], 0, s[36:37]
	v_lshl_add_u64 v[70:71], s[4:5], 0, v[70:71]
	v_lshl_add_u64 v[74:75], s[6:7], 0, v[50:51]
	global_load_dwordx4 v[128:131], v[72:73], off
	global_load_dwordx4 v[136:139], v[74:75], off
	v_lshl_add_u64 v[50:51], s[4:5], 0, v[50:51]
	global_load_dwordx4 v[132:135], v[70:71], off
	global_load_dwordx4 v[140:143], v[50:51], off
	v_mov_b32_e32 v78, v77
	s_nop 1
	v_permlane32_swap_b32_e32 v77, v78
	v_max_f32_e32 v50, v78, v78
	v_max_f32_e32 v51, v77, v77
	v_max_f32_e32 v50, v51, v50
	v_add_f32_e32 v51, 0x7149f2ca, v50
	v_max_f32_e32 v50, 0xf149f2ca, v50
	v_cmp_ge_f32_e32 vcc, s14, v51
	v_sub_f32_e32 v51, 0xf149f2ca, v50
	v_mul_f32_e32 v51, 0x3e0293ee, v51
	v_exp_f32_e32 v51, v51
	s_cmp_eq_u64 vcc, exec
	s_cselect_b64 vcc, -1, 0
	v_cndmask_b32_e32 v164, v50, v180, vcc
	v_mul_f32_e32 v50, 0xbe0293ee, v164
	v_cndmask_b32_e64 v200, v51, 1.0, vcc
	v_mov_b32_e32 v51, v50
	v_fmamk_f32 v32, v32, 0x3e0293ee, v50
	v_fmamk_f32 v33, v33, 0x3e0293ee, v50
	v_fmamk_f32 v34, v34, 0x3e0293ee, v50
	v_fmamk_f32 v35, v35, 0x3e0293ee, v50
	v_fmamk_f32 v36, v36, 0x3e0293ee, v50
	v_fmamk_f32 v37, v37, 0x3e0293ee, v50
	v_fmamk_f32 v38, v38, 0x3e0293ee, v50
	v_fmamk_f32 v39, v39, 0x3e0293ee, v50
	v_fmamk_f32 v40, v40, 0x3e0293ee, v50
	v_fmamk_f32 v41, v41, 0x3e0293ee, v50
	v_fmamk_f32 v42, v42, 0x3e0293ee, v50
	v_fmamk_f32 v43, v43, 0x3e0293ee, v50
	v_fmamk_f32 v44, v44, 0x3e0293ee, v50
	v_fmamk_f32 v45, v45, 0x3e0293ee, v50
	v_fmamk_f32 v46, v46, 0x3e0293ee, v50
	v_fmac_f32_e32 v51, 0x3e0293ee, v47
	v_pk_fma_f32 v[154:155], v[18:19], s[10:11], v[50:51] op_sel_hi:[1,0,0]
	v_pk_fma_f32 v[156:157], v[16:17], s[10:11], v[50:51] op_sel_hi:[1,0,0]
	v_exp_f32_e32 v161, v32
	v_exp_f32_e32 v162, v33
	v_exp_f32_e32 v174, v34
	v_exp_f32_e32 v175, v35
	v_exp_f32_e32 v204, v36
	v_exp_f32_e32 v207, v37
	v_exp_f32_e32 v163, v38
	v_exp_f32_e32 v173, v39
	v_exp_f32_e32 v168, v40
	v_exp_f32_e32 v170, v41
	v_exp_f32_e32 v171, v42
	v_exp_f32_e32 v172, v43
	v_exp_f32_e32 v165, v44
	v_exp_f32_e32 v166, v45
	v_exp_f32_e32 v167, v46
	v_exp_f32_e32 v169, v51
	v_mad_i64_i32 v[16:17], s[4:5], s16, v181, v[48:49]
	v_and_b32_e32 v18, 15, v52
	s_waitcnt vmcnt(4)
; #define SBAR() __builtin_amdgcn_sched_barrier(0)
; #define SWAIT() do { if constexpr (SDEPTH == 2) asm volatile("s_waitcnt vmcnt(4)" ::: "memory"); else asm volatile("s_waitcnt vmcnt(0)" ::: "memory"); } while (0)
; __device__ __forceinline__ void finishSM(f32x16& p0, f32x16& p1, float alpha, float& l_reg, bf16x8& pa0, bf16x8& pa1, bf16x8& pa2, bf16x8& pa3) {
;   for (int r = 0; r < 16; ++r) p1[r] = __builtin_amdgcn_exp2f(p1[r]);
;   float ps = 0; for (int r = 0; r < 16; ++r) ps += p0[r]; for (int r = 0; r < 16; ++r) ps += p1[r];
;   { auto rr = __builtin_amdgcn_permlane32_swap(__float_as_uint(ps), __float_as_uint(ps), false, false);
;     ps = __uint_as_float(rr[0]) + __uint_as_float(rr[1]); }
;   l_reg = l_reg * alpha + ps;
;     ...
;   PK4(p0, 0, pa0); PK4(p0, 8, pa1); PK4(p1, 0, pa2); PK4(p1, 8, pa3);
;     ...
; }
; template <typename TQ>
; __device__ __forceinline__ void attn_dense_body(const TQ* __restrict__ Qb, const bf16* __restrict__ Kh, const bf16* __restrict__ Vh,
;                                                 bf16* __restrict__ Ob, int seq, char* lds, const int tid) {
;     ...
;   SWAIT(); SWRITE(1, SO); __syncthreads();
;   for (int j = 1; j + 1 < NT; j += 2) {
;     SBAR(); qkt(pB0, pB1, (bf16*)((char*)K_lds + SHM_K), qr, r32, hi);
;     finishSM(pA0, pA1, alA, l_reg, pa0, pa1, pa2, pa3); SBAR();
	s_addk_i32 s9, 0x4000
	v_lshl_or_b32 v16, v18, 4, v16
	v_mov_b64_e32 v[12:13], s[68:69]
	v_pk_fma_f32 v[150:151], v[30:31], s[10:11], v[50:51] op_sel_hi:[1,0,0]
	v_pk_fma_f32 v[152:153], v[28:29], s[10:11], v[50:51] op_sel_hi:[1,0,0]
	v_pk_fma_f32 v[158:159], v[26:27], s[10:11], v[50:51] op_sel_hi:[1,0,0]
	v_pk_fma_f32 v[144:145], v[24:25], s[10:11], v[50:51] op_sel_hi:[1,0,0]
	v_pk_fma_f32 v[146:147], v[22:23], s[10:11], v[50:51] op_sel_hi:[1,0,0]
	v_pk_fma_f32 v[148:149], v[20:21], s[10:11], v[50:51] op_sel_hi:[1,0,0]
	s_waitcnt vmcnt(7)
	ds_write_b128 v188, v[54:57] offset:16384
	s_waitcnt vmcnt(6)
	ds_write_b128 v189, v[58:61] offset:16384
	s_waitcnt vmcnt(5)
	ds_write_b128 v190, v[62:65] offset:49152
	s_waitcnt vmcnt(4)
	ds_write_b128 v191, v[66:69] offset:49152
	v_add_u32_e32 v186, s9, v53
	v_lshl_add_u64 v[178:179], s[0:1], 0, v[16:17]
	v_mov_b64_e32 v[62:63], v[14:15]
	v_mov_b64_e32 v[46:47], v[14:15]
	v_mov_b64_e32 v[30:31], v[14:15]
	v_cmp_gt_u32_e64 s[36:37], 32, v76
	v_mov_b64_e32 v[60:61], v[12:13]
	v_mov_b64_e32 v[58:59], v[10:11]
	v_mov_b64_e32 v[56:57], v[8:9]
	v_mov_b64_e32 v[54:55], v[6:7]
	v_mov_b64_e32 v[52:53], v[4:5]
	v_mov_b64_e32 v[50:51], v[2:3]
	v_mov_b64_e32 v[48:49], v[0:1]
	v_mov_b64_e32 v[44:45], v[12:13]
	v_mov_b64_e32 v[42:43], v[10:11]
	v_mov_b64_e32 v[40:41], v[8:9]
	v_mov_b64_e32 v[38:39], v[6:7]
	v_mov_b64_e32 v[36:37], v[4:5]
	v_mov_b64_e32 v[34:35], v[2:3]
	v_mov_b64_e32 v[32:33], v[0:1]
	v_mov_b64_e32 v[28:29], v[12:13]
	v_mov_b64_e32 v[26:27], v[10:11]
	v_mov_b64_e32 v[24:25], v[8:9]
	v_mov_b64_e32 v[22:23], v[6:7]
	v_mov_b64_e32 v[20:21], v[4:5]
	v_mov_b64_e32 v[18:19], v[2:3]
	v_mov_b64_e32 v[16:17], v[0:1]
	s_mov_b32 s9, 1
	s_waitcnt lgkmcnt(0)
	s_barrier
.LBB0_1529:
	ds_read_b128 v[64:67], v192 offset:49152
	ds_read_b128 v[68:71], v192 offset:57344
	ds_read_b128 v[208:211], v199 offset:49152
	ds_read_b128 v[212:215], v199 offset:57344
	v_add_f32_e32 v160, 0, v161
	v_add_f32_e32 v160, v162, v160
	s_waitcnt lgkmcnt(3)
	v_mfma_f32_32x32x16_bf16 v[80:95], v[64:67], v[120:123], 0
	v_add_f32_e32 v160, v174, v160
	v_add_f32_e32 v160, v175, v160
	v_add_f32_e32 v160, v204, v160
	v_add_f32_e32 v160, v207, v160
	v_add_f32_e32 v160, v163, v160
	v_add_f32_e32 v160, v173, v160
	v_add_f32_e32 v160, v168, v160
	s_waitcnt lgkmcnt(2)
	v_mfma_f32_32x32x16_bf16 v[64:79], v[68:71], v[120:123], 0
	v_add_f32_e32 v160, v170, v160
	v_add_f32_e32 v160, v171, v160
	v_add_f32_e32 v160, v172, v160
	v_exp_f32_e32 v156, v156
	v_add_f32_e32 v160, v165, v160
	v_exp_f32_e32 v157, v157
	v_add_f32_e32 v160, v166, v160
	s_waitcnt lgkmcnt(1)
	v_mfma_f32_32x32x16_bf16 v[80:95], v[208:211], v[112:115], v[80:95]
	v_exp_f32_e32 v154, v154
	v_add_f32_e32 v160, v167, v160
	v_exp_f32_e32 v155, v155
	v_add_f32_e32 v160, v169, v160
	v_exp_f32_e32 v148, v148
	v_add_f32_e32 v160, v156, v160
	v_exp_f32_e32 v149, v149
	s_waitcnt lgkmcnt(0)
	v_mfma_f32_32x32x16_bf16 v[64:79], v[212:215], v[112:115], v[64:79]
	ds_read_b128 v[208:211], v198 offset:49152
	ds_read_b128 v[212:215], v198 offset:57344
	v_add_f32_e32 v160, v157, v160
	v_exp_f32_e32 v146, v146
	v_add_f32_e32 v160, v154, v160
	v_exp_f32_e32 v147, v147
	v_add_f32_e32 v160, v155, v160
	v_exp_f32_e32 v144, v144
	s_waitcnt lgkmcnt(1)
	v_mfma_f32_32x32x16_bf16 v[80:95], v[208:211], v[124:127], v[80:95]
	v_add_f32_e32 v160, v148, v160
	v_exp_f32_e32 v145, v145
	v_add_f32_e32 v160, v149, v160
	v_exp_f32_e32 v158, v158
	v_add_f32_e32 v160, v146, v160
	v_exp_f32_e32 v159, v159
	v_add_f32_e32 v160, v147, v160
	s_waitcnt lgkmcnt(0)
	v_mfma_f32_32x32x16_bf16 v[64:79], v[212:215], v[124:127], v[64:79]
	ds_read_b128 v[208:211], v195 offset:49152
	ds_read_b128 v[212:215], v195 offset:57344
	v_exp_f32_e32 v152, v152
	v_add_f32_e32 v160, v144, v160
	v_exp_f32_e32 v153, v153
	v_add_f32_e32 v160, v145, v160
	v_exp_f32_e32 v150, v150
	v_add_f32_e32 v160, v158, v160
	s_waitcnt lgkmcnt(1)
	v_mfma_f32_32x32x16_bf16 v[80:95], v[208:211], v[116:119], v[80:95]
	v_exp_f32_e32 v151, v151
	v_add_f32_e32 v160, v159, v160
	v_add_f32_e32 v160, v152, v160
	v_add_f32_e32 v160, v153, v160
	v_add_f32_e32 v160, v150, v160
	v_add_f32_e32 v201, v151, v160
	v_mov_b32_e32 v202, v201
	s_waitcnt lgkmcnt(0)
	v_mfma_f32_32x32x16_bf16 v[64:79], v[212:215], v[116:119], v[64:79]
	ds_read_b128 v[208:211], v194 offset:49152
	ds_read_b128 v[212:215], v194 offset:57344
	v_cvt_pk_bf16_f32 v160, v161, v162
	v_cvt_pk_bf16_f32 v162, v204, v207
	v_permlane32_swap_b32_e32 v201, v202
	v_cvt_pk_bf16_f32 v161, v174, v175
	v_cvt_pk_bf16_f32 v163, v163, v173
	s_waitcnt lgkmcnt(1)
	v_mfma_f32_32x32x16_bf16 v[80:95], v[208:211], v[108:111], v[80:95]
	v_cvt_pk_bf16_f32 v170, v168, v170
	v_cvt_pk_bf16_f32 v171, v171, v172
	v_cvt_pk_bf16_f32 v172, v165, v166
	v_cvt_pk_bf16_f32 v173, v167, v169
	v_cvt_pk_bf16_f32 v166, v156, v157
	s_waitcnt lgkmcnt(0)
	v_mfma_f32_32x32x16_bf16 v[64:79], v[212:215], v[108:111], v[64:79]
	ds_read_b128 v[208:211], v193 offset:49152
	ds_read_b128 v[212:215], v193 offset:57344
	v_cvt_pk_bf16_f32 v167, v154, v155
	v_cvt_pk_bf16_f32 v168, v148, v149
	v_cvt_pk_bf16_f32 v169, v146, v147
	v_cvt_pk_bf16_f32 v204, v144, v145
	v_cvt_pk_bf16_f32 v205, v158, v159
	v_cvt_pk_bf16_f32 v206, v152, v153
	s_waitcnt lgkmcnt(1)
	v_mfma_f32_32x32x16_bf16 v[80:95], v[208:211], v[104:107], v[80:95]
	v_cvt_pk_bf16_f32 v207, v150, v151
	s_waitcnt lgkmcnt(0)
	v_mfma_f32_32x32x16_bf16 v[64:79], v[212:215], v[104:107], v[64:79]
	ds_read_b128 v[208:211], v196 offset:49152
	ds_read_b128 v[212:215], v196 offset:57344
	s_waitcnt lgkmcnt(1)
	v_mfma_f32_32x32x16_bf16 v[80:95], v[208:211], v[100:103], v[80:95]
	s_waitcnt lgkmcnt(0)
; #define SBAR() __builtin_amdgcn_sched_barrier(0)
; #define SLOAD(i, k0) do { sr_[i].vs0 = St::ld8(&Vh[(long)((k0) + sr) * LDK + sc]); sr_[i].vs1 = St::ld8(&Vh[(long)((k0) + 32 + sr) * LDK + sc]); \
;     sr_[i].ks0 = St::ld8(&Kh[(long)((k0) + sr) * LDK + sc]); sr_[i].ks1 = St::ld8(&Kh[(long)((k0) + 32 + sr) * LDK + sc]); } while (0)
; #define SWAIT() do { if constexpr (SDEPTH == 2) asm volatile("s_waitcnt vmcnt(4)" ::: "memory"); else asm volatile("s_waitcnt vmcnt(0)" ::: "memory"); } while (0)
; template <int OFF> __device__ __forceinline__ s16x4 tr_read(int vb) {
;   s16x4 r; asm volatile("ds_read_b64_tr_b16 %0, %1 offset:%2" : "=&v"(r) : "v"(vb), "i"(OFF) : "memory"); return r;
; }
; template <int D0> __device__ __forceinline__ void pv_one(f32x16& od, int vb, bf16x8 pa0, bf16x8 pa1, bf16x8 pa2, bf16x8 pa3) {
;   const s16x4 l0 = tr_read<v_rd_off(D0, 0, 0)>(vb), h0 = tr_read<v_rd_off(D0, 0, 1)>(vb), l1 = tr_read<v_rd_off(D0, 1, 0)>(vb), h1 = tr_read<v_rd_off(D0, 1, 1)>(vb);
;   const s16x4 l2 = tr_read<v_rd_off(D0, 2, 0)>(vb), h2 = tr_read<v_rd_off(D0, 2, 1)>(vb), l3 = tr_read<v_rd_off(D0, 3, 0)>(vb), h3 = tr_read<v_rd_off(D0, 3, 1)>(vb);
;   asm volatile("s_waitcnt lgkmcnt(0)" ::: "memory"); SBAR();
;     ...
;   od = __builtin_amdgcn_mfma_f32_32x32x16_bf16(pa0, PK(l0, h0), od, 0, 0, 0);
;   od = __builtin_amdgcn_mfma_f32_32x32x16_bf16(pa1, PK(l1, h1), od, 0, 0, 0);
;   od = __builtin_amdgcn_mfma_f32_32x32x16_bf16(pa2, PK(l2, h2), od, 0, 0, 0);
;   od = __builtin_amdgcn_mfma_f32_32x32x16_bf16(pa3, PK(l3, h3), od, 0, 0, 0);
;     ...
; }
; __device__ __forceinline__ void pv_d0(f32x16* o, int vb, bf16x8 pa0, bf16x8 pa1, bf16x8 pa2, bf16x8 pa3) {
;   pv_one<0>(o[0], vb, pa0, pa1, pa2, pa3); pv_one<1>(o[1], vb, pa0, pa1, pa2, pa3); pv_one<2>(o[2], vb, pa0, pa1, pa2, pa3); pv_one<3>(o[3], vb, pa0, pa1, pa2, pa3);
; template <typename TQ>
; __device__ __forceinline__ void attn_dense_body(const TQ* __restrict__ Qb, const bf16* __restrict__ Kh, const bf16* __restrict__ Vh,
;                                                 bf16* __restrict__ Ob, int seq, char* lds, const int tid) {
;     ...
;     SLOAD(SO, (j + SDEPTH) * KVBLK); SBAR();
;     pv_d0(o, vb0, pa0, pa1, pa2, pa3); partialSM(pB0, pB1, m_reg, mnB, alB);
;     __syncthreads(); SWAIT(); SWRITE(0, SE);
;     RESC(alB); __syncthreads();
	v_mfma_f32_32x32x16_bf16 v[64:79], v[212:215], v[100:103], v[64:79]
	ds_read_b128 v[208:211], v197 offset:49152
	ds_read_b128 v[212:215], v197 offset:57344
	s_waitcnt lgkmcnt(1)
	v_mfma_f32_32x32x16_bf16 v[80:95], v[208:211], v[96:99], v[80:95]
	s_waitcnt lgkmcnt(0)
	v_mfma_f32_32x32x16_bf16 v[64:79], v[212:215], v[96:99], v[64:79]
	s_movk_i32 s4, 0xa000
	v_add_co_u32_e32 v144, vcc, s4, v178
	s_movk_i32 s4, 0xc000
	s_nop 0
	v_addc_co_u32_e32 v145, vcc, -1, v179, vcc
	v_add_co_u32_e32 v148, vcc, s4, v178
	s_mov_b32 s4, 0xe53fa000
	s_nop 0
	v_addc_co_u32_e32 v149, vcc, -1, v179, vcc
	v_add_co_u32_e32 v152, vcc, s4, v178
	s_mov_b32 s4, 0xe53fc000
	s_nop 0
	v_addc_co_u32_e32 v153, vcc, -1, v179, vcc
	v_add_co_u32_e32 v156, vcc, s4, v178
	global_load_dwordx4 v[144:147], v[144:145], off
	s_nop 0
	global_load_dwordx4 v[148:151], v[148:149], off
	v_addc_co_u32_e32 v157, vcc, -1, v179, vcc
	global_load_dwordx4 v[152:155], v[152:153], off
	s_nop 0
	global_load_dwordx4 v[156:159], v[156:157], off
	ds_read_b64_tr_b16 v[208:209], v187 offset:0
	ds_read_b64_tr_b16 v[210:211], v187 offset:0x800
	ds_read_b64_tr_b16 v[212:213], v187 offset:0x1000
	ds_read_b64_tr_b16 v[214:215], v187 offset:0x1800
	ds_read_b64_tr_b16 v[218:219], v187 offset:0x2000
	ds_read_b64_tr_b16 v[220:221], v187 offset:0x2800
	ds_read_b64_tr_b16 v[222:223], v187 offset:0x3000
	ds_read_b64_tr_b16 v[224:225], v187 offset:0x3800
	s_waitcnt lgkmcnt(0)
	s_nop 0
	v_mfma_f32_32x32x16_bf16 v[0:15], v[160:163], v[208:211], v[0:15]
	ds_read_b64_tr_b16 v[208:209], v187 offset:0x200
	ds_read_b64_tr_b16 v[210:211], v187 offset:0xa00
	v_mfma_f32_32x32x16_bf16 v[0:15], v[170:173], v[212:215], v[0:15]
	ds_read_b64_tr_b16 v[212:213], v187 offset:0x1200
	ds_read_b64_tr_b16 v[214:215], v187 offset:0x1a00
	v_mfma_f32_32x32x16_bf16 v[0:15], v[166:169], v[218:221], v[0:15]
	ds_read_b64_tr_b16 v[218:219], v187 offset:0x2200
	ds_read_b64_tr_b16 v[220:221], v187 offset:0x2a00
	v_mfma_f32_32x32x16_bf16 v[0:15], v[204:207], v[222:225], v[0:15]
	ds_read_b64_tr_b16 v[222:223], v187 offset:0x3200
	ds_read_b64_tr_b16 v[224:225], v187 offset:0x3a00
	s_waitcnt lgkmcnt(0)
	v_mfma_f32_32x32x16_bf16 v[48:63], v[160:163], v[208:211], v[48:63]
	ds_read_b64_tr_b16 v[208:209], v187 offset:0x400
	ds_read_b64_tr_b16 v[210:211], v187 offset:0xc00
	v_mfma_f32_32x32x16_bf16 v[48:63], v[170:173], v[212:215], v[48:63]
	ds_read_b64_tr_b16 v[212:213], v187 offset:0x1400
	ds_read_b64_tr_b16 v[214:215], v187 offset:0x1c00
	v_mfma_f32_32x32x16_bf16 v[48:63], v[166:169], v[218:221], v[48:63]
	ds_read_b64_tr_b16 v[218:219], v187 offset:0x2400
	ds_read_b64_tr_b16 v[220:221], v187 offset:0x2c00
	v_mfma_f32_32x32x16_bf16 v[48:63], v[204:207], v[222:225], v[48:63]
	ds_read_b64_tr_b16 v[222:223], v187 offset:0x3400
	ds_read_b64_tr_b16 v[224:225], v187 offset:0x3c00
	s_waitcnt lgkmcnt(0)
	v_mfma_f32_32x32x16_bf16 v[32:47], v[160:163], v[208:211], v[32:47]
	ds_read_b64_tr_b16 v[208:209], v187 offset:0x600
	ds_read_b64_tr_b16 v[210:211], v187 offset:0xe00
	v_mfma_f32_32x32x16_bf16 v[32:47], v[170:173], v[212:215], v[32:47]
	ds_read_b64_tr_b16 v[212:213], v187 offset:0x1600
	ds_read_b64_tr_b16 v[214:215], v187 offset:0x1e00
	v_mfma_f32_32x32x16_bf16 v[32:47], v[166:169], v[218:221], v[32:47]
	ds_read_b64_tr_b16 v[218:219], v187 offset:0x2600
	ds_read_b64_tr_b16 v[220:221], v187 offset:0x2e00
	v_mfma_f32_32x32x16_bf16 v[32:47], v[204:207], v[222:225], v[32:47]
	ds_read_b64_tr_b16 v[222:223], v187 offset:0x3600
	ds_read_b64_tr_b16 v[224:225], v187 offset:0x3e00
	s_waitcnt lgkmcnt(0)
	v_mfma_f32_32x32x16_bf16 v[16:31], v[160:163], v[208:211], v[16:31]
	v_max_f32_e32 v160, v81, v81
	v_max_f32_e32 v161, v80, v80
	v_max_f32_e32 v160, v161, v160
	v_max3_f32 v160, v160, v82, v83
	v_max3_f32 v160, v160, v84, v85
	v_max3_f32 v160, v160, v86, v87
	v_max3_f32 v160, v160, v88, v89
	v_max3_f32 v160, v160, v90, v91
	v_max3_f32 v160, v160, v92, v93
	v_mfma_f32_32x32x16_bf16 v[16:31], v[170:173], v[212:215], v[16:31]
	v_max3_f32 v160, v160, v94, v95
	v_max3_f32 v160, v160, v64, v65
	v_max3_f32 v160, v160, v66, v67
	v_max3_f32 v160, v160, v68, v69
	v_max3_f32 v160, v160, v70, v71
	v_max3_f32 v160, v160, v72, v73
	v_max3_f32 v160, v160, v74, v75
	v_max3_f32 v160, v160, v76, v77
	v_mfma_f32_32x32x16_bf16 v[16:31], v[166:169], v[218:221], v[16:31]
	v_max3_f32 v160, v160, v78, v79
	v_mov_b32_e32 v161, v160
	s_nop 1
	v_permlane32_swap_b32_e32 v160, v161
	v_max_f32_e32 v161, v161, v161
	v_max_f32_e32 v160, v160, v160
	v_max_f32_e32 v160, v160, v161
	v_sub_f32_e32 v161, v160, v164
	v_cmp_ge_f32_e32 vcc, s14, v161
	v_max_f32_e32 v161, v164, v164
	v_max_f32_e32 v160, v161, v160
	v_mfma_f32_32x32x16_bf16 v[16:31], v[204:207], v[222:225], v[16:31]
	v_sub_f32_e32 v161, v164, v160
	v_mul_f32_e32 v161, 0x3e0293ee, v161
	v_exp_f32_e32 v161, v161
	s_cmp_eq_u64 vcc, exec
	s_cselect_b64 s[38:39], -1, 0
	s_barrier
	s_waitcnt vmcnt(4)
	v_cndmask_b32_e64 v203, v161, 1.0, s[38:39]
	v_cmp_gt_f32_e32 vcc, 1.0, v203
	s_waitcnt vmcnt(7)
	ds_write_b128 v188, v[128:131]
	s_waitcnt vmcnt(6)
	ds_write_b128 v189, v[136:139]
	s_waitcnt vmcnt(5)
	ds_write_b128 v190, v[132:135] offset:32768
	s_waitcnt vmcnt(4)
	ds_write_b128 v191, v[140:143] offset:32768
	s_cbranch_vccz .LBB0_1533
	s_and_saveexec_b64 s[4:5], s[36:37]
	ds_write_b32 v184, v203 offset:128
	s_or_b64 exec, exec, s[4:5]
	s_waitcnt lgkmcnt(0)
	v_add_u32_e32 v161, s8, v176
	ds_read_b128 v[166:169], v161 offset:224
	ds_read_b128 v[170:173], v161 offset:192
	ds_read_b128 v[204:207], v161 offset:160
	ds_read_b128 v[208:211], v161 offset:128
	s_waitcnt lgkmcnt(3)
	v_pk_mul_f32 v[12:13], v[12:13], v[166:167]
	s_waitcnt lgkmcnt(2)
	v_pk_mul_f32 v[8:9], v[8:9], v[170:171]
	s_waitcnt lgkmcnt(1)
	v_pk_mul_f32 v[4:5], v[4:5], v[204:205]
	v_pk_mul_f32 v[14:15], v[14:15], v[168:169]
	v_pk_mul_f32 v[10:11], v[10:11], v[172:173]
	v_pk_mul_f32 v[6:7], v[6:7], v[206:207]
	s_waitcnt lgkmcnt(0)
	v_pk_mul_f32 v[2:3], v[2:3], v[210:211]
	v_pk_mul_f32 v[0:1], v[0:1], v[208:209]
	v_pk_mul_f32 v[60:61], v[60:61], v[166:167]
	v_pk_mul_f32 v[56:57], v[56:57], v[170:171]
	v_pk_mul_f32 v[52:53], v[52:53], v[204:205]
	v_pk_mul_f32 v[62:63], v[62:63], v[168:169]
	v_pk_mul_f32 v[58:59], v[58:59], v[172:173]
	v_pk_mul_f32 v[54:55], v[54:55], v[206:207]
	v_pk_mul_f32 v[50:51], v[50:51], v[210:211]
	v_pk_mul_f32 v[48:49], v[48:49], v[208:209]
	v_pk_mul_f32 v[44:45], v[44:45], v[166:167]
	v_pk_mul_f32 v[40:41], v[40:41], v[170:171]
	v_pk_mul_f32 v[36:37], v[36:37], v[204:205]
	v_pk_mul_f32 v[46:47], v[46:47], v[168:169]
	v_pk_mul_f32 v[42:43], v[42:43], v[172:173]
	v_pk_mul_f32 v[38:39], v[38:39], v[206:207]
	v_pk_mul_f32 v[34:35], v[34:35], v[210:211]
	v_pk_mul_f32 v[32:33], v[32:33], v[208:209]
	v_pk_mul_f32 v[28:29], v[28:29], v[166:167]
	v_pk_mul_f32 v[24:25], v[24:25], v[170:171]
	v_pk_mul_f32 v[20:21], v[20:21], v[204:205]
	v_pk_mul_f32 v[30:31], v[30:31], v[168:169]
	v_pk_mul_f32 v[26:27], v[26:27], v[172:173]
	v_pk_mul_f32 v[22:23], v[22:23], v[206:207]
	v_pk_mul_f32 v[18:19], v[18:19], v[210:211]
	v_pk_mul_f32 v[16:17], v[16:17], v[208:209]
; #define SBAR() __builtin_amdgcn_sched_barrier(0)
; #define SLOAD(i, k0) do { sr_[i].vs0 = St::ld8(&Vh[(long)((k0) + sr) * LDK + sc]); sr_[i].vs1 = St::ld8(&Vh[(long)((k0) + 32 + sr) * LDK + sc]); \
;     sr_[i].ks0 = St::ld8(&Kh[(long)((k0) + sr) * LDK + sc]); sr_[i].ks1 = St::ld8(&Kh[(long)((k0) + 32 + sr) * LDK + sc]); } while (0)
; __device__ __forceinline__ void partialSM(f32x16& p0, f32x16& p1, float& m_reg, float& mn, float& alpha) {
;   constexpr float C = SCALE * 1.4426950408889634f;
;   float pmax = p0[0]; for (int r = 1; r < 16; ++r) pmax = fmaxf(pmax, p0[r]); for (int r = 0; r < 16; ++r) pmax = fmaxf(pmax, p1[r]);
;   { auto rr = __builtin_amdgcn_permlane32_swap(__float_as_uint(pmax), __float_as_uint(pmax), false, false);
;     pmax = fmaxf(__uint_as_float(rr[0]), __uint_as_float(rr[1])); }
;   if (__builtin_expect(__all(pmax - m_reg <= THR / SCALE), 1)) { mn = m_reg; alpha = 1.f; }
;   else { mn = fmaxf(m_reg, pmax); alpha = __builtin_amdgcn_exp2f((m_reg - mn) * C); m_reg = mn; }
;   float mnC = -mn * C;
;   for (int r = 0; r < 16; ++r) p0[r] = fmaf(p0[r], C, mnC); for (int r = 0; r < 16; ++r) p1[r] = fmaf(p1[r], C, mnC);
;   for (int r = 0; r < 16; ++r) p0[r] = __builtin_amdgcn_exp2f(p0[r]);
; }
; __device__ __forceinline__ void finishSM(f32x16& p0, f32x16& p1, float alpha, float& l_reg, bf16x8& pa0, bf16x8& pa1, bf16x8& pa2, bf16x8& pa3) {
;   for (int r = 0; r < 16; ++r) p1[r] = __builtin_amdgcn_exp2f(p1[r]);
;   float ps = 0; for (int r = 0; r < 16; ++r) ps += p0[r]; for (int r = 0; r < 16; ++r) ps += p1[r];
;   { auto rr = __builtin_amdgcn_permlane32_swap(__float_as_uint(ps), __float_as_uint(ps), false, false);
;     ps = __uint_as_float(rr[0]) + __uint_as_float(rr[1]); }
;   l_reg = l_reg * alpha + ps;
;     ...
;   PK4(p0, 0, pa0); PK4(p0, 8, pa1); PK4(p1, 0, pa2); PK4(p1, 8, pa3);
;     ...
; }
; template <typename TQ>
; __device__ __forceinline__ void attn_dense_body(const TQ* __restrict__ Qb, const bf16* __restrict__ Kh, const bf16* __restrict__ Vh,
;                                                 bf16* __restrict__ Ob, int seq, char* lds, const int tid) {
;     ...
;     RESC(alB); __syncthreads();
;     SBAR(); qkt(pA0, pA1, K_lds, qr, r32, hi);
;     finishSM(pB0, pB1, alB, l_reg, pa0, pa1, pa2, pa3); SBAR();
;     if (SDEPTH == 1 || j + 3 < NT) SLOAD(SE, (j + 1 + SDEPTH) * KVBLK); SBAR();
.LBB0_1533:
	v_cndmask_b32_e64 v204, v160, v164, s[38:39]
	v_mul_f32_e32 v205, 0xbe0293ee, v204
	v_fmamk_f32 v80, v80, 0x3e0293ee, v205
	v_fmamk_f32 v81, v81, 0x3e0293ee, v205
	v_fmamk_f32 v82, v82, 0x3e0293ee, v205
	v_fmamk_f32 v83, v83, 0x3e0293ee, v205
	v_fmamk_f32 v84, v84, 0x3e0293ee, v205
	v_fmamk_f32 v85, v85, 0x3e0293ee, v205
	v_fmamk_f32 v86, v86, 0x3e0293ee, v205
	v_fmamk_f32 v87, v87, 0x3e0293ee, v205
	v_fmamk_f32 v88, v88, 0x3e0293ee, v205
	v_fmamk_f32 v89, v89, 0x3e0293ee, v205
	v_fmamk_f32 v90, v90, 0x3e0293ee, v205
	v_fmamk_f32 v91, v91, 0x3e0293ee, v205
	v_fmamk_f32 v92, v92, 0x3e0293ee, v205
	v_fmamk_f32 v93, v93, 0x3e0293ee, v205
	v_fmamk_f32 v94, v94, 0x3e0293ee, v205
	v_fmamk_f32 v95, v95, 0x3e0293ee, v205
	v_exp_f32_e32 v160, v80
	v_exp_f32_e32 v161, v81
	v_exp_f32_e32 v162, v82
	v_exp_f32_e32 v173, v83
	v_exp_f32_e32 v174, v84
	v_exp_f32_e32 v175, v85
	v_exp_f32_e32 v163, v86
	v_exp_f32_e32 v172, v87
	v_exp_f32_e32 v164, v88
	v_exp_f32_e32 v165, v89
	v_exp_f32_e32 v170, v90
	v_exp_f32_e32 v171, v91
	v_exp_f32_e32 v166, v92
	v_exp_f32_e32 v167, v93
	v_exp_f32_e32 v168, v94
	v_exp_f32_e32 v169, v95
	v_fmamk_f32 v214, v64, 0x3e0293ee, v205
	v_fmamk_f32 v215, v65, 0x3e0293ee, v205
	v_fmamk_f32 v217, v66, 0x3e0293ee, v205
	v_fmamk_f32 v218, v67, 0x3e0293ee, v205
	v_fmamk_f32 v219, v68, 0x3e0293ee, v205
	v_fmamk_f32 v207, v69, 0x3e0293ee, v205
	v_fmamk_f32 v208, v70, 0x3e0293ee, v205
	v_fmamk_f32 v209, v71, 0x3e0293ee, v205
	v_fmamk_f32 v210, v72, 0x3e0293ee, v205
	v_fmamk_f32 v211, v73, 0x3e0293ee, v205
	v_fmamk_f32 v212, v74, 0x3e0293ee, v205
	v_fmamk_f32 v213, v75, 0x3e0293ee, v205
	v_fmamk_f32 v206, v76, 0x3e0293ee, v205
	v_fmamk_f32 v220, v77, 0x3e0293ee, v205
	v_fmamk_f32 v221, v78, 0x3e0293ee, v205
	v_fmac_f32_e32 v205, 0x3e0293ee, v79
	s_waitcnt lgkmcnt(0)
	s_barrier
	ds_read_b128 v[64:67], v192 offset:32768
	ds_read_b128 v[68:71], v192 offset:40960
	ds_read_b128 v[222:225], v199 offset:32768
	ds_read_b128 v[226:229], v199 offset:40960
	v_exp_f32_e32 v214, v214
	v_exp_f32_e32 v215, v215
	s_waitcnt lgkmcnt(3)
	v_mfma_f32_32x32x16_bf16 v[80:95], v[64:67], v[120:123], 0
	v_exp_f32_e32 v217, v217
	v_exp_f32_e32 v218, v218
	v_exp_f32_e32 v219, v219
	v_exp_f32_e32 v207, v207
	v_exp_f32_e32 v208, v208
	v_exp_f32_e32 v209, v209
	v_exp_f32_e32 v210, v210
	s_waitcnt lgkmcnt(2)
	v_mfma_f32_32x32x16_bf16 v[64:79], v[68:71], v[120:123], 0
	v_exp_f32_e32 v211, v211
	v_exp_f32_e32 v212, v212
	v_exp_f32_e32 v213, v213
	v_exp_f32_e32 v220, v220
	v_exp_f32_e32 v221, v221
	s_waitcnt lgkmcnt(1)
	v_mfma_f32_32x32x16_bf16 v[80:95], v[222:225], v[112:115], v[80:95]
	s_waitcnt lgkmcnt(0)
	v_mfma_f32_32x32x16_bf16 v[64:79], v[226:229], v[112:115], v[64:79]
	ds_read_b128 v[222:225], v198 offset:32768
	ds_read_b128 v[226:229], v198 offset:40960
	s_waitcnt lgkmcnt(1)
	v_mfma_f32_32x32x16_bf16 v[80:95], v[222:225], v[124:127], v[80:95]
	s_waitcnt lgkmcnt(0)
	v_mfma_f32_32x32x16_bf16 v[64:79], v[226:229], v[124:127], v[64:79]
	ds_read_b128 v[222:225], v195 offset:32768
	ds_read_b128 v[226:229], v195 offset:40960
	s_waitcnt lgkmcnt(1)
	v_mfma_f32_32x32x16_bf16 v[80:95], v[222:225], v[116:119], v[80:95]
	s_waitcnt lgkmcnt(0)
	v_mfma_f32_32x32x16_bf16 v[64:79], v[226:229], v[116:119], v[64:79]
	ds_read_b128 v[222:225], v194 offset:32768
	ds_read_b128 v[226:229], v194 offset:40960
	s_waitcnt lgkmcnt(1)
	v_mfma_f32_32x32x16_bf16 v[80:95], v[222:225], v[108:111], v[80:95]
	s_waitcnt lgkmcnt(0)
	v_mfma_f32_32x32x16_bf16 v[64:79], v[226:229], v[108:111], v[64:79]
	ds_read_b128 v[222:225], v193 offset:32768
	ds_read_b128 v[226:229], v193 offset:40960
	s_waitcnt lgkmcnt(1)
	v_mfma_f32_32x32x16_bf16 v[80:95], v[222:225], v[104:107], v[80:95]
	s_waitcnt lgkmcnt(0)
	v_mfma_f32_32x32x16_bf16 v[64:79], v[226:229], v[104:107], v[64:79]
	ds_read_b128 v[222:225], v196 offset:32768
	ds_read_b128 v[226:229], v196 offset:40960
	s_waitcnt lgkmcnt(1)
	v_mfma_f32_32x32x16_bf16 v[80:95], v[222:225], v[100:103], v[80:95]
	s_waitcnt lgkmcnt(0)
	v_mfma_f32_32x32x16_bf16 v[64:79], v[226:229], v[100:103], v[64:79]
	ds_read_b128 v[222:225], v197 offset:32768
	ds_read_b128 v[226:229], v197 offset:40960
	s_waitcnt lgkmcnt(1)
	v_mfma_f32_32x32x16_bf16 v[80:95], v[222:225], v[96:99], v[80:95]
	v_exp_f32_e32 v223, v205
	v_add_f32_e32 v205, 0, v160
	v_add_f32_e32 v205, v161, v205
	v_add_f32_e32 v205, v162, v205
	v_add_f32_e32 v205, v173, v205
	v_add_f32_e32 v205, v174, v205
	v_add_f32_e32 v205, v175, v205
	v_add_f32_e32 v205, v163, v205
	v_add_f32_e32 v205, v172, v205
	v_add_f32_e32 v205, v164, v205
	v_add_f32_e32 v205, v165, v205
	v_add_f32_e32 v205, v170, v205
	v_add_f32_e32 v205, v171, v205
	v_add_f32_e32 v205, v166, v205
	v_add_f32_e32 v205, v167, v205
	v_add_f32_e32 v205, v168, v205
	v_add_f32_e32 v205, v169, v205
	v_add_f32_e32 v205, v214, v205
	v_add_f32_e32 v205, v215, v205
	v_add_f32_e32 v205, v217, v205
	v_add_f32_e32 v205, v218, v205
	v_add_f32_e32 v205, v219, v205
	v_add_f32_e32 v205, v207, v205
	v_add_f32_e32 v205, v208, v205
	v_add_f32_e32 v205, v209, v205
	v_exp_f32_e32 v222, v206
	v_add_f32_e32 v205, v210, v205
	v_add_f32_e32 v205, v211, v205
	s_waitcnt lgkmcnt(0)
	v_mfma_f32_32x32x16_bf16 v[64:79], v[226:229], v[96:99], v[64:79]
	v_add_f32_e32 v205, v212, v205
	v_add_f32_e32 v205, v213, v205
	v_add_f32_e32 v205, v222, v205
	v_add_f32_e32 v205, v220, v205
	v_add_f32_e32 v205, v221, v205
	v_add_f32_e32 v205, v223, v205
	v_mov_b32_e32 v206, v205
	v_cvt_pk_bf16_f32 v160, v160, v161
	v_cvt_pk_bf16_f32 v161, v162, v173
	v_cvt_pk_bf16_f32 v162, v174, v175
	v_cvt_pk_bf16_f32 v163, v163, v172
	v_cvt_pk_bf16_f32 v164, v164, v165
	v_cvt_pk_bf16_f32 v165, v170, v171
	v_cvt_pk_bf16_f32 v166, v166, v167
	v_cvt_pk_bf16_f32 v167, v168, v169
	v_cvt_pk_bf16_f32 v168, v214, v215
	v_cvt_pk_bf16_f32 v169, v217, v218
	v_cvt_pk_bf16_f32 v170, v219, v207
	v_cvt_pk_bf16_f32 v171, v208, v209
	v_cvt_pk_bf16_f32 v172, v210, v211
	v_cvt_pk_bf16_f32 v173, v212, v213
	v_cvt_pk_bf16_f32 v174, v222, v220
	v_cvt_pk_bf16_f32 v175, v221, v223
	v_permlane32_swap_b32_e32 v205, v206
	s_cmp_gt_u32 s9, 64
	s_cselect_b64 s[4:5], -1, 0
	s_and_b64 vcc, exec, s[4:5]
	s_cbranch_vccnz .LBB0_1535
	v_add_co_u32_e32 v128, vcc, 0xffffe000, v178
	s_nop 1
	v_addc_co_u32_e32 v129, vcc, -1, v179, vcc
	v_add_co_u32_e32 v132, vcc, 0xe53fe000, v178
	s_nop 1
	v_addc_co_u32_e32 v133, vcc, -1, v179, vcc
	v_add_co_u32_e32 v140, vcc, 0xe5400000, v178
	global_load_dwordx4 v[128:131], v[128:129], off
	s_nop 0
	global_load_dwordx4 v[132:135], v[132:133], off
	v_addc_co_u32_e32 v141, vcc, -1, v179, vcc
	global_load_dwordx4 v[136:139], v[178:179], off
	s_nop 0
	global_load_dwordx4 v[140:143], v[140:141], off

; #define SBAR() __builtin_amdgcn_sched_barrier(0)
; __device__ __forceinline__ void finishSM(f32x16& p0, f32x16& p1, float alpha, float& l_reg, bf16x8& pa0, bf16x8& pa1, bf16x8& pa2, bf16x8& pa3) {
;   for (int r = 0; r < 16; ++r) p1[r] = __builtin_amdgcn_exp2f(p1[r]);
;   float ps = 0; for (int r = 0; r < 16; ++r) ps += p0[r]; for (int r = 0; r < 16; ++r) ps += p1[r];
;   { auto rr = __builtin_amdgcn_permlane32_swap(__float_as_uint(ps), __float_as_uint(ps), false, false);
;     ps = __uint_as_float(rr[0]) + __uint_as_float(rr[1]); }
;   l_reg = l_reg * alpha + ps;
;     ...
;   PK4(p0, 0, pa0); PK4(p0, 8, pa1); PK4(p1, 0, pa2); PK4(p1, 8, pa3);
;     ...
; }
; template <typename TQ>
; __device__ __forceinline__ void attn_dense_body(const TQ* __restrict__ Qb, const bf16* __restrict__ Kh, const bf16* __restrict__ Vh,
;                                                 bf16* __restrict__ Ob, int seq, char* lds, const int tid) {
;     ...
;   SBAR(); qkt(pB0, pB1, (bf16*)((char*)K_lds + SHM_K), qr, r32, hi);
;   finishSM(pA0, pA1, alA, l_reg, pa0, pa1, pa2, pa3); SBAR();
;   pv_d0(o, vb0, pa0, pa1, pa2, pa3); partialSM(pB0, pB1, m_reg, mnB, alB);
.LBB0_1541:
	ds_read_b128 v[64:67], v192 offset:49152
	ds_read_b128 v[68:71], v192 offset:57344
	s_waitcnt lgkmcnt(1)
	v_mfma_f32_32x32x16_bf16 v[80:95], v[64:67], v[120:123], 0
	s_waitcnt lgkmcnt(0)
	v_mfma_f32_32x32x16_bf16 v[64:79], v[68:71], v[120:123], 0
	ds_read_b128 v[120:123], v199 offset:49152
	ds_read_b128 v[128:131], v199 offset:57344
	s_waitcnt lgkmcnt(1)
	v_mfma_f32_32x32x16_bf16 v[80:95], v[120:123], v[112:115], v[80:95]
	s_waitcnt lgkmcnt(0)
	v_mfma_f32_32x32x16_bf16 v[64:79], v[128:131], v[112:115], v[64:79]
	ds_read_b128 v[112:115], v198 offset:49152
	ds_read_b128 v[120:123], v198 offset:57344
	s_waitcnt lgkmcnt(1)
	v_mfma_f32_32x32x16_bf16 v[80:95], v[112:115], v[124:127], v[80:95]
	s_waitcnt lgkmcnt(0)
	v_mfma_f32_32x32x16_bf16 v[64:79], v[120:123], v[124:127], v[64:79]
	ds_read_b128 v[112:115], v195 offset:49152
	ds_read_b128 v[120:123], v195 offset:57344
	s_waitcnt lgkmcnt(1)
	v_mfma_f32_32x32x16_bf16 v[80:95], v[112:115], v[116:119], v[80:95]
	s_waitcnt lgkmcnt(0)
	v_mfma_f32_32x32x16_bf16 v[64:79], v[120:123], v[116:119], v[64:79]
	ds_read_b128 v[112:115], v194 offset:49152
	ds_read_b128 v[116:119], v194 offset:57344
	v_exp_f32_e32 v120, v150
	v_exp_f32_e32 v121, v151
	s_waitcnt lgkmcnt(1)
	v_mfma_f32_32x32x16_bf16 v[80:95], v[112:115], v[108:111], v[80:95]
	s_waitcnt lgkmcnt(0)
	v_mfma_f32_32x32x16_bf16 v[64:79], v[116:119], v[108:111], v[64:79]
	ds_read_b128 v[108:111], v193 offset:49152
	ds_read_b128 v[112:115], v193 offset:57344
	v_exp_f32_e32 v116, v158
	v_exp_f32_e32 v117, v159
	v_exp_f32_e32 v118, v152
	v_exp_f32_e32 v119, v153
	s_waitcnt lgkmcnt(1)
	v_mfma_f32_32x32x16_bf16 v[80:95], v[108:111], v[104:107], v[80:95]
	s_waitcnt lgkmcnt(0)
	v_mfma_f32_32x32x16_bf16 v[64:79], v[112:115], v[104:107], v[64:79]
	ds_read_b128 v[104:107], v196 offset:49152
	ds_read_b128 v[108:111], v196 offset:57344
	v_exp_f32_e32 v112, v146
	v_exp_f32_e32 v113, v147
	v_exp_f32_e32 v114, v144
	v_exp_f32_e32 v115, v145
	s_waitcnt lgkmcnt(1)
	v_mfma_f32_32x32x16_bf16 v[80:95], v[104:107], v[100:103], v[80:95]
	s_waitcnt lgkmcnt(0)
	v_mfma_f32_32x32x16_bf16 v[64:79], v[108:111], v[100:103], v[64:79]
	ds_read_b128 v[100:103], v197 offset:49152
	ds_read_b128 v[104:107], v197 offset:57344
	v_exp_f32_e32 v108, v154
	v_exp_f32_e32 v109, v155
	v_exp_f32_e32 v110, v148
	v_exp_f32_e32 v111, v149
	s_waitcnt lgkmcnt(1)
	v_mfma_f32_32x32x16_bf16 v[80:95], v[100:103], v[96:99], v[80:95]
	v_cvt_pk_bf16_f32 v100, v204, v207
	v_cvt_pk_bf16_f32 v101, v163, v173
	v_cvt_pk_bf16_f32 v102, v168, v170
	v_cvt_pk_bf16_f32 v103, v171, v172
	s_waitcnt lgkmcnt(0)
	v_mfma_f32_32x32x16_bf16 v[64:79], v[104:107], v[96:99], v[64:79]
	v_add_f32_e32 v96, 0, v161
	v_add_f32_e32 v96, v162, v96
	v_add_f32_e32 v96, v174, v96
	v_add_f32_e32 v96, v175, v96
	v_add_f32_e32 v96, v204, v96
	v_add_f32_e32 v96, v207, v96
	v_add_f32_e32 v96, v163, v96
	v_add_f32_e32 v96, v173, v96
	v_add_f32_e32 v96, v168, v96
	v_add_f32_e32 v96, v170, v96
	v_add_f32_e32 v96, v171, v96
	v_add_f32_e32 v96, v172, v96
	v_exp_f32_e32 v106, v156
	v_add_f32_e32 v96, v165, v96
	v_exp_f32_e32 v107, v157
	v_add_f32_e32 v96, v166, v96
	v_add_f32_e32 v96, v167, v96
	v_add_f32_e32 v96, v169, v96
	v_add_f32_e32 v96, v106, v96
	v_add_f32_e32 v96, v107, v96
	v_add_f32_e32 v96, v108, v96
	v_add_f32_e32 v96, v109, v96
	v_add_f32_e32 v96, v110, v96
	v_add_f32_e32 v96, v111, v96
	v_add_f32_e32 v96, v112, v96
	v_add_f32_e32 v96, v113, v96
	v_add_f32_e32 v96, v114, v96
	v_add_f32_e32 v96, v115, v96
	v_add_f32_e32 v96, v116, v96
	v_add_f32_e32 v96, v117, v96
	v_add_f32_e32 v96, v118, v96
	v_add_f32_e32 v96, v119, v96
	v_add_f32_e32 v96, v120, v96
	v_add_f32_e32 v96, v121, v96
	v_mov_b32_e32 v97, v96
	v_cvt_pk_bf16_f32 v98, v161, v162
	v_cvt_pk_bf16_f32 v99, v174, v175
	v_permlane32_swap_b32_e32 v96, v97
	v_cvt_pk_bf16_f32 v104, v165, v166
	v_cvt_pk_bf16_f32 v105, v167, v169
	v_cvt_pk_bf16_f32 v106, v106, v107
	v_cvt_pk_bf16_f32 v107, v108, v109
	v_cvt_pk_bf16_f32 v108, v110, v111
	v_cvt_pk_bf16_f32 v109, v112, v113
	v_cvt_pk_bf16_f32 v110, v114, v115
	v_cvt_pk_bf16_f32 v111, v116, v117
	v_cvt_pk_bf16_f32 v112, v118, v119
	v_cvt_pk_bf16_f32 v113, v120, v121
	ds_read_b64_tr_b16 v[114:115], v187 offset:0
	ds_read_b64_tr_b16 v[116:117], v187 offset:0x800
	ds_read_b64_tr_b16 v[118:119], v187 offset:0x1000
	ds_read_b64_tr_b16 v[120:121], v187 offset:0x1800
	ds_read_b64_tr_b16 v[122:123], v187 offset:0x2000
	ds_read_b64_tr_b16 v[124:125], v187 offset:0x2800
	ds_read_b64_tr_b16 v[126:127], v187 offset:0x3000
	ds_read_b64_tr_b16 v[128:129], v187 offset:0x3800
	s_waitcnt lgkmcnt(0)
	s_nop 0
	v_mfma_f32_32x32x16_bf16 v[0:15], v[98:101], v[114:117], v[0:15]
	ds_read_b64_tr_b16 v[114:115], v187 offset:0x200
	ds_read_b64_tr_b16 v[116:117], v187 offset:0xa00
	v_mfma_f32_32x32x16_bf16 v[0:15], v[102:105], v[118:121], v[0:15]
	ds_read_b64_tr_b16 v[118:119], v187 offset:0x1200
	ds_read_b64_tr_b16 v[120:121], v187 offset:0x1a00
	v_mfma_f32_32x32x16_bf16 v[0:15], v[106:109], v[122:125], v[0:15]
	ds_read_b64_tr_b16 v[122:123], v187 offset:0x2200
	ds_read_b64_tr_b16 v[124:125], v187 offset:0x2a00
	v_mfma_f32_32x32x16_bf16 v[0:15], v[110:113], v[126:129], v[0:15]
	ds_read_b64_tr_b16 v[126:127], v187 offset:0x3200
	ds_read_b64_tr_b16 v[128:129], v187 offset:0x3a00
	s_waitcnt lgkmcnt(0)
	v_mfma_f32_32x32x16_bf16 v[48:63], v[98:101], v[114:117], v[48:63]
	ds_read_b64_tr_b16 v[114:115], v187 offset:0x400
	ds_read_b64_tr_b16 v[116:117], v187 offset:0xc00
	v_mfma_f32_32x32x16_bf16 v[48:63], v[102:105], v[118:121], v[48:63]
	ds_read_b64_tr_b16 v[118:119], v187 offset:0x1400
	ds_read_b64_tr_b16 v[120:121], v187 offset:0x1c00
	v_mfma_f32_32x32x16_bf16 v[48:63], v[106:109], v[122:125], v[48:63]
	ds_read_b64_tr_b16 v[122:123], v187 offset:0x2400
	ds_read_b64_tr_b16 v[124:125], v187 offset:0x2c00
	v_mfma_f32_32x32x16_bf16 v[48:63], v[110:113], v[126:129], v[48:63]
	ds_read_b64_tr_b16 v[126:127], v187 offset:0x3400
	ds_read_b64_tr_b16 v[128:129], v187 offset:0x3c00
	s_waitcnt lgkmcnt(0)
; #define SBAR() __builtin_amdgcn_sched_barrier(0)
; #define RESC(a) do { if (__any((a) < 1.f)) { if (hi == 0) al_l[r32] = (a); asm volatile("s_waitcnt lgkmcnt(0)" ::: "memory"); \
;     for (int d = 0; d < 4; ++d) for (int r = 0; r < 16; ++r) o[d][r] *= al_l[crow(r, hi)]; } } while (0)
; template <int D0> __device__ __forceinline__ void pv_one(f32x16& od, int vb, bf16x8 pa0, bf16x8 pa1, bf16x8 pa2, bf16x8 pa3) {
;   const s16x4 l0 = tr_read<v_rd_off(D0, 0, 0)>(vb), h0 = tr_read<v_rd_off(D0, 0, 1)>(vb), l1 = tr_read<v_rd_off(D0, 1, 0)>(vb), h1 = tr_read<v_rd_off(D0, 1, 1)>(vb);
;   const s16x4 l2 = tr_read<v_rd_off(D0, 2, 0)>(vb), h2 = tr_read<v_rd_off(D0, 2, 1)>(vb), l3 = tr_read<v_rd_off(D0, 3, 0)>(vb), h3 = tr_read<v_rd_off(D0, 3, 1)>(vb);
;   asm volatile("s_waitcnt lgkmcnt(0)" ::: "memory"); SBAR();
;     ...
;   od = __builtin_amdgcn_mfma_f32_32x32x16_bf16(pa0, PK(l0, h0), od, 0, 0, 0);
;   od = __builtin_amdgcn_mfma_f32_32x32x16_bf16(pa1, PK(l1, h1), od, 0, 0, 0);
;   od = __builtin_amdgcn_mfma_f32_32x32x16_bf16(pa2, PK(l2, h2), od, 0, 0, 0);
;   od = __builtin_amdgcn_mfma_f32_32x32x16_bf16(pa3, PK(l3, h3), od, 0, 0, 0);
;     ...
; }
; __device__ __forceinline__ void pv_d0(f32x16* o, int vb, bf16x8 pa0, bf16x8 pa1, bf16x8 pa2, bf16x8 pa3) {
;   pv_one<0>(o[0], vb, pa0, pa1, pa2, pa3); pv_one<1>(o[1], vb, pa0, pa1, pa2, pa3); pv_one<2>(o[2], vb, pa0, pa1, pa2, pa3); pv_one<3>(o[3], vb, pa0, pa1, pa2, pa3);
; template <typename TQ>
; __device__ __forceinline__ void attn_dense_body(const TQ* __restrict__ Qb, const bf16* __restrict__ Kh, const bf16* __restrict__ Vh,
;                                                 bf16* __restrict__ Ob, int seq, char* lds, const int tid) {
;     ...
;   pv_d0(o, vb0, pa0, pa1, pa2, pa3); partialSM(pB0, pB1, m_reg, mnB, alB);
;   __syncthreads(); RESC(alB);
	v_mfma_f32_32x32x16_bf16 v[32:47], v[98:101], v[114:117], v[32:47]
	ds_read_b64_tr_b16 v[114:115], v187 offset:0x600
	ds_read_b64_tr_b16 v[116:117], v187 offset:0xe00
	v_mfma_f32_32x32x16_bf16 v[32:47], v[102:105], v[118:121], v[32:47]
	ds_read_b64_tr_b16 v[118:119], v187 offset:0x1600
	ds_read_b64_tr_b16 v[120:121], v187 offset:0x1e00
	v_mfma_f32_32x32x16_bf16 v[32:47], v[106:109], v[122:125], v[32:47]
	ds_read_b64_tr_b16 v[122:123], v187 offset:0x2600
	ds_read_b64_tr_b16 v[124:125], v187 offset:0x2e00
	v_mfma_f32_32x32x16_bf16 v[32:47], v[110:113], v[126:129], v[32:47]
	ds_read_b64_tr_b16 v[126:127], v187 offset:0x3600
	ds_read_b64_tr_b16 v[128:129], v187 offset:0x3e00
	s_waitcnt lgkmcnt(0)
	v_mfma_f32_32x32x16_bf16 v[16:31], v[98:101], v[114:117], v[16:31]
	v_max_f32_e32 v98, v81, v81
	v_max_f32_e32 v99, v80, v80
	v_max_f32_e32 v98, v99, v98
	v_max3_f32 v98, v98, v82, v83
	v_max3_f32 v98, v98, v84, v85
	v_max3_f32 v98, v98, v86, v87
	v_max3_f32 v98, v98, v88, v89
	v_max3_f32 v98, v98, v90, v91
	v_max3_f32 v98, v98, v92, v93
	v_mfma_f32_32x32x16_bf16 v[16:31], v[102:105], v[118:121], v[16:31]
	v_max3_f32 v98, v98, v94, v95
	v_max3_f32 v98, v98, v64, v65
	v_max3_f32 v98, v98, v66, v67
	v_max3_f32 v98, v98, v68, v69
	v_max3_f32 v98, v98, v70, v71
	v_max3_f32 v98, v98, v72, v73
	v_max3_f32 v98, v98, v74, v75
	v_max3_f32 v98, v98, v76, v77
	v_mfma_f32_32x32x16_bf16 v[16:31], v[106:109], v[122:125], v[16:31]
	v_max3_f32 v98, v98, v78, v79
	v_mov_b32_e32 v99, v98
	s_nop 1
	v_permlane32_swap_b32_e32 v98, v99
	v_max_f32_e32 v99, v99, v99
	v_max_f32_e32 v98, v98, v98
	v_max_f32_e32 v98, v98, v99
	v_sub_f32_e32 v99, v98, v164
	v_cmp_ge_f32_e32 vcc, s14, v99
	v_max_f32_e32 v99, v164, v164
	v_max_f32_e32 v99, v99, v98
	v_mfma_f32_32x32x16_bf16 v[16:31], v[110:113], v[126:129], v[16:31]
	v_sub_f32_e32 v98, v164, v99
	v_mul_f32_e32 v98, 0x3e0293ee, v98
	v_exp_f32_e32 v98, v98
	s_cmp_eq_u64 vcc, exec
	s_cselect_b64 s[38:39], -1, 0
	v_cndmask_b32_e64 v98, v98, 1.0, s[38:39]
	v_cmp_gt_f32_e32 vcc, 1.0, v98
	s_barrier
	s_cbranch_vccz .LBB0_1545
	s_and_saveexec_b64 s[4:5], s[36:37]
	ds_write_b32 v184, v98 offset:128
	s_or_b64 exec, exec, s[4:5]
	s_waitcnt lgkmcnt(0)
	v_add_u32_e32 v112, s8, v176
	ds_read_b128 v[100:103], v112 offset:224
	ds_read_b128 v[104:107], v112 offset:192
	ds_read_b128 v[108:111], v112 offset:160
	ds_read_b128 v[112:115], v112 offset:128
	s_waitcnt lgkmcnt(3)
	v_pk_mul_f32 v[12:13], v[12:13], v[100:101]
	s_waitcnt lgkmcnt(2)
	v_pk_mul_f32 v[8:9], v[8:9], v[104:105]
	s_waitcnt lgkmcnt(1)
	v_pk_mul_f32 v[4:5], v[4:5], v[108:109]
	v_pk_mul_f32 v[14:15], v[14:15], v[102:103]
	v_pk_mul_f32 v[10:11], v[10:11], v[106:107]
	v_pk_mul_f32 v[6:7], v[6:7], v[110:111]
	s_waitcnt lgkmcnt(0)
	v_pk_mul_f32 v[2:3], v[2:3], v[114:115]
	v_pk_mul_f32 v[0:1], v[0:1], v[112:113]
	v_pk_mul_f32 v[60:61], v[60:61], v[100:101]
	v_pk_mul_f32 v[56:57], v[56:57], v[104:105]
	v_pk_mul_f32 v[52:53], v[52:53], v[108:109]
	v_pk_mul_f32 v[62:63], v[62:63], v[102:103]
	v_pk_mul_f32 v[58:59], v[58:59], v[106:107]
	v_pk_mul_f32 v[54:55], v[54:55], v[110:111]
	v_pk_mul_f32 v[50:51], v[50:51], v[114:115]
	v_pk_mul_f32 v[48:49], v[48:49], v[112:113]
	v_pk_mul_f32 v[44:45], v[44:45], v[100:101]
	v_pk_mul_f32 v[40:41], v[40:41], v[104:105]
	v_pk_mul_f32 v[36:37], v[36:37], v[108:109]
	v_pk_mul_f32 v[46:47], v[46:47], v[102:103]
	v_pk_mul_f32 v[42:43], v[42:43], v[106:107]
	v_pk_mul_f32 v[38:39], v[38:39], v[110:111]
	v_pk_mul_f32 v[34:35], v[34:35], v[114:115]
	v_pk_mul_f32 v[32:33], v[32:33], v[112:113]
	v_pk_mul_f32 v[28:29], v[28:29], v[100:101]
	v_pk_mul_f32 v[24:25], v[24:25], v[104:105]
	v_pk_mul_f32 v[20:21], v[20:21], v[108:109]
	v_pk_mul_f32 v[30:31], v[30:31], v[102:103]
	v_pk_mul_f32 v[26:27], v[26:27], v[106:107]
	v_pk_mul_f32 v[22:23], v[22:23], v[110:111]
	v_pk_mul_f32 v[18:19], v[18:19], v[114:115]
	v_pk_mul_f32 v[16:17], v[16:17], v[112:113]
; #define SBAR() __builtin_amdgcn_sched_barrier(0)
; #define RESC(a) do { if (__any((a) < 1.f)) { if (hi == 0) al_l[r32] = (a); asm volatile("s_waitcnt lgkmcnt(0)" ::: "memory"); \
;     for (int d = 0; d < 4; ++d) for (int r = 0; r < 16; ++r) o[d][r] *= al_l[crow(r, hi)]; } } while (0)
; __device__ __forceinline__ void finishSM(f32x16& p0, f32x16& p1, float alpha, float& l_reg, bf16x8& pa0, bf16x8& pa1, bf16x8& pa2, bf16x8& pa3) {
;   for (int r = 0; r < 16; ++r) p1[r] = __builtin_amdgcn_exp2f(p1[r]);
;   float ps = 0; for (int r = 0; r < 16; ++r) ps += p0[r]; for (int r = 0; r < 16; ++r) ps += p1[r];
;   { auto rr = __builtin_amdgcn_permlane32_swap(__float_as_uint(ps), __float_as_uint(ps), false, false);
;     ps = __uint_as_float(rr[0]) + __uint_as_float(rr[1]); }
;   l_reg = l_reg * alpha + ps;
;     ...
;   PK4(p0, 0, pa0); PK4(p0, 8, pa1); PK4(p1, 0, pa2); PK4(p1, 8, pa3);
;     ...
; }
; template <typename TQ>
; __device__ __forceinline__ void attn_dense_body(const TQ* __restrict__ Qb, const bf16* __restrict__ Kh, const bf16* __restrict__ Vh,
;                                                 bf16* __restrict__ Ob, int seq, char* lds, const int tid) {
;     ...
;   __syncthreads(); RESC(alB);
;   finishSM(pB0, pB1, alB, l_reg, pa0, pa1, pa2, pa3); SBAR();
;   pv_d0(o, vb0 + (int)SHM_V, pa0, pa1, pa2, pa3);
;   if (hi == 0) li_l[r32] = l_reg; asm volatile("s_waitcnt lgkmcnt(0)" ::: "memory");
.LBB0_1545:
	v_cndmask_b32_e64 v99, v99, v164, s[38:39]
	v_mul_f32_e32 v99, 0xbe0293ee, v99
	v_fmamk_f32 v80, v80, 0x3e0293ee, v99
	v_fmamk_f32 v81, v81, 0x3e0293ee, v99
	v_fmamk_f32 v108, v93, 0x3e0293ee, v99
	v_fmamk_f32 v93, v74, 0x3e0293ee, v99
	v_exp_f32_e32 v74, v80
	v_fmamk_f32 v82, v82, 0x3e0293ee, v99
	v_fmamk_f32 v109, v94, 0x3e0293ee, v99
	v_fmamk_f32 v94, v75, 0x3e0293ee, v99
	v_exp_f32_e32 v75, v81
	v_fmamk_f32 v83, v83, 0x3e0293ee, v99
	v_fmamk_f32 v110, v95, 0x3e0293ee, v99
	v_fmamk_f32 v95, v76, 0x3e0293ee, v99
	v_exp_f32_e32 v76, v82
	v_fmamk_f32 v84, v84, 0x3e0293ee, v99
	v_fmamk_f32 v64, v64, 0x3e0293ee, v99
	v_exp_f32_e32 v80, v83
	v_fmamk_f32 v100, v85, 0x3e0293ee, v99
	v_fmamk_f32 v101, v86, 0x3e0293ee, v99
	v_fmamk_f32 v102, v87, 0x3e0293ee, v99
	v_fmamk_f32 v103, v88, 0x3e0293ee, v99
	v_fmamk_f32 v104, v89, 0x3e0293ee, v99
	v_fmamk_f32 v105, v90, 0x3e0293ee, v99
	v_fmamk_f32 v106, v91, 0x3e0293ee, v99
	v_fmamk_f32 v107, v92, 0x3e0293ee, v99
	v_fmamk_f32 v65, v65, 0x3e0293ee, v99
	v_fmamk_f32 v85, v66, 0x3e0293ee, v99
	v_fmamk_f32 v86, v67, 0x3e0293ee, v99
	v_fmamk_f32 v87, v68, 0x3e0293ee, v99
	v_fmamk_f32 v88, v69, 0x3e0293ee, v99
	v_fmamk_f32 v89, v70, 0x3e0293ee, v99
	v_fmamk_f32 v90, v71, 0x3e0293ee, v99
	v_fmamk_f32 v91, v72, 0x3e0293ee, v99
	v_fmamk_f32 v92, v73, 0x3e0293ee, v99
	v_exp_f32_e32 v81, v84
	v_fmamk_f32 v77, v77, 0x3e0293ee, v99
	v_fmamk_f32 v78, v78, 0x3e0293ee, v99
	v_fmac_f32_e32 v99, 0x3e0293ee, v79
	v_exp_f32_e32 v79, v64
	v_add_f32_e32 v64, 0, v74
	v_exp_f32_e32 v82, v100
	v_add_f32_e32 v64, v75, v64
	v_exp_f32_e32 v83, v101
	v_add_f32_e32 v64, v76, v64
	v_exp_f32_e32 v84, v102
	v_add_f32_e32 v64, v80, v64
	v_exp_f32_e32 v66, v103
	v_add_f32_e32 v64, v81, v64
	v_exp_f32_e32 v67, v104
	v_add_f32_e32 v64, v82, v64
	v_exp_f32_e32 v68, v105
	v_add_f32_e32 v64, v83, v64
	v_exp_f32_e32 v69, v106
	v_add_f32_e32 v64, v84, v64
	v_exp_f32_e32 v70, v107
	v_add_f32_e32 v64, v66, v64
	v_exp_f32_e32 v71, v108
	v_add_f32_e32 v64, v67, v64
	v_exp_f32_e32 v72, v109
	v_add_f32_e32 v64, v68, v64
	v_exp_f32_e32 v73, v110
	v_add_f32_e32 v64, v69, v64
	v_add_f32_e32 v64, v70, v64
	v_exp_f32_e32 v100, v65
	v_add_f32_e32 v64, v71, v64
	v_exp_f32_e32 v85, v85
	v_add_f32_e32 v64, v72, v64
	v_exp_f32_e32 v86, v86
	v_add_f32_e32 v64, v73, v64
	v_exp_f32_e32 v87, v87
	v_add_f32_e32 v64, v79, v64
	v_exp_f32_e32 v88, v88
	v_add_f32_e32 v64, v100, v64
	v_exp_f32_e32 v89, v89
	v_add_f32_e32 v64, v85, v64
	v_exp_f32_e32 v90, v90
	v_add_f32_e32 v64, v86, v64
	v_exp_f32_e32 v91, v91
	v_add_f32_e32 v64, v87, v64
	v_exp_f32_e32 v92, v92
	v_add_f32_e32 v64, v88, v64
	v_exp_f32_e32 v93, v93
	v_add_f32_e32 v64, v89, v64
	v_exp_f32_e32 v94, v94
	v_add_f32_e32 v64, v90, v64
	v_exp_f32_e32 v95, v95
	v_add_f32_e32 v64, v91, v64
	v_exp_f32_e32 v101, v77
	v_add_f32_e32 v64, v92, v64
	v_exp_f32_e32 v102, v78
	v_add_f32_e32 v64, v93, v64
	v_exp_f32_e32 v99, v99
	v_add_f32_e32 v64, v94, v64
	v_add_f32_e32 v64, v95, v64
	v_add_f32_e32 v64, v101, v64
	v_add_f32_e32 v64, v102, v64
	v_add_f32_e32 v64, v99, v64
	v_mov_b32_e32 v65, v64
	s_nop 1
	v_permlane32_swap_b32_e32 v64, v65
	v_cvt_pk_bf16_f32 v74, v74, v75
	v_cvt_pk_bf16_f32 v75, v76, v80
	v_cvt_pk_bf16_f32 v76, v81, v82
	v_cvt_pk_bf16_f32 v77, v83, v84
	v_cvt_pk_bf16_f32 v66, v66, v67
	v_cvt_pk_bf16_f32 v67, v68, v69
	v_cvt_pk_bf16_f32 v68, v70, v71
	v_cvt_pk_bf16_f32 v69, v72, v73
	v_cvt_pk_bf16_f32 v70, v79, v100
	v_cvt_pk_bf16_f32 v71, v85, v86
	v_cvt_pk_bf16_f32 v72, v87, v88
	v_cvt_pk_bf16_f32 v73, v89, v90
	v_cvt_pk_bf16_f32 v78, v91, v92
	v_cvt_pk_bf16_f32 v79, v93, v94
	v_cvt_pk_bf16_f32 v80, v95, v101
	v_cvt_pk_bf16_f32 v81, v102, v99
	ds_read_b64_tr_b16 v[82:83], v186 offset:0
	ds_read_b64_tr_b16 v[84:85], v186 offset:0x800
	ds_read_b64_tr_b16 v[86:87], v186 offset:0x1000
	ds_read_b64_tr_b16 v[88:89], v186 offset:0x1800
	ds_read_b64_tr_b16 v[90:91], v186 offset:0x2000
	ds_read_b64_tr_b16 v[92:93], v186 offset:0x2800
	ds_read_b64_tr_b16 v[100:101], v186 offset:0x3000
	ds_read_b64_tr_b16 v[102:103], v186 offset:0x3800
	s_waitcnt lgkmcnt(0)
	s_nop 0
	v_mfma_f32_32x32x16_bf16 v[0:15], v[74:77], v[82:85], v[0:15]
	ds_read_b64_tr_b16 v[82:83], v186 offset:0x200
	ds_read_b64_tr_b16 v[84:85], v186 offset:0xa00
	v_mfma_f32_32x32x16_bf16 v[0:15], v[66:69], v[86:89], v[0:15]
	ds_read_b64_tr_b16 v[86:87], v186 offset:0x1200
	ds_read_b64_tr_b16 v[88:89], v186 offset:0x1a00
	v_mfma_f32_32x32x16_bf16 v[0:15], v[70:73], v[90:93], v[0:15]
	ds_read_b64_tr_b16 v[90:91], v186 offset:0x2200
	ds_read_b64_tr_b16 v[92:93], v186 offset:0x2a00
	v_mfma_f32_32x32x16_bf16 v[0:15], v[78:81], v[100:103], v[0:15]
	ds_read_b64_tr_b16 v[100:101], v186 offset:0x3200
	ds_read_b64_tr_b16 v[102:103], v186 offset:0x3a00
	s_waitcnt lgkmcnt(0)
	v_mfma_f32_32x32x16_bf16 v[48:63], v[74:77], v[82:85], v[48:63]
	ds_read_b64_tr_b16 v[82:83], v186 offset:0x400
	ds_read_b64_tr_b16 v[84:85], v186 offset:0xc00
	v_mfma_f32_32x32x16_bf16 v[48:63], v[66:69], v[86:89], v[48:63]
	ds_read_b64_tr_b16 v[86:87], v186 offset:0x1400
	ds_read_b64_tr_b16 v[88:89], v186 offset:0x1c00
	v_mfma_f32_32x32x16_bf16 v[48:63], v[70:73], v[90:93], v[48:63]
	ds_read_b64_tr_b16 v[90:91], v186 offset:0x2400
	ds_read_b64_tr_b16 v[92:93], v186 offset:0x2c00
	v_mfma_f32_32x32x16_bf16 v[48:63], v[78:81], v[100:103], v[48:63]
	ds_read_b64_tr_b16 v[100:101], v186 offset:0x3400
	ds_read_b64_tr_b16 v[102:103], v186 offset:0x3c00
	s_waitcnt lgkmcnt(0)
	v_mfma_f32_32x32x16_bf16 v[32:47], v[74:77], v[82:85], v[32:47]
	ds_read_b64_tr_b16 v[82:83], v186 offset:0x600
	ds_read_b64_tr_b16 v[84:85], v186 offset:0xe00
	v_mfma_f32_32x32x16_bf16 v[32:47], v[66:69], v[86:89], v[32:47]
	ds_read_b64_tr_b16 v[86:87], v186 offset:0x1600
	ds_read_b64_tr_b16 v[88:89], v186 offset:0x1e00
	v_mfma_f32_32x32x16_bf16 v[32:47], v[70:73], v[90:93], v[32:47]
	ds_read_b64_tr_b16 v[90:91], v186 offset:0x2600
	ds_read_b64_tr_b16 v[92:93], v186 offset:0x2e00
	v_mfma_f32_32x32x16_bf16 v[32:47], v[78:81], v[100:103], v[32:47]
	ds_read_b64_tr_b16 v[100:101], v186 offset:0x3600
	ds_read_b64_tr_b16 v[102:103], v186 offset:0x3e00
	s_waitcnt lgkmcnt(0)
	v_mfma_f32_32x32x16_bf16 v[16:31], v[74:77], v[82:85], v[16:31]
	v_mfma_f32_32x32x16_bf16 v[16:31], v[66:69], v[86:89], v[16:31]
	v_mfma_f32_32x32x16_bf16 v[16:31], v[70:73], v[90:93], v[16:31]
	v_mfma_f32_32x32x16_bf16 v[16:31], v[78:81], v[100:103], v[16:31]
	s_and_saveexec_b64 s[4:5], s[36:37]
	s_cbranch_execz .LBB0_1527
	v_add_f32_e32 v66, v96, v97
	v_fmac_f32_e32 v66, v185, v160
	v_add_f32_e32 v64, v64, v65
	v_fmac_f32_e32 v64, v66, v98
	ds_write_b32 v184, v64
	s_branch .LBB0_1527
